# rsl row-scale cache per row tile + barrier L1 invalidate issued at arrival
# baseline (speedup 1.0000x reference)
; __global__ void __launch_bounds__(NTHR, 2) hybrid_fwd(Args args) {
;     ...
;     for (int step = -1; step < 5 * DEPTH; ++step) {
;         const int l = step < 0 ? 0 : step / 5, ph = step < 0 ? -1 : step % 5;
;         int cvt_layer = -1, cvt_first = 0, cvt_n = 0, cvt_nu = 0;
;         if (ph < 0) {
.LBB0_10:
	s_mov_b32 s100, -1
	s_cmp_lt_i32 s97, 0
	s_cselect_b64 s[6:7], -1, 0
	s_cmp_gt_i32 s97, -1
	s_mov_b64 s[0:1], -1
	s_cbranch_scc1 .LBB0_13
	s_and_b64 vcc, exec, s[0:1]
	s_cbranch_vccnz .LBB0_315

;     __device__ __forceinline__ void operator()(f32x4 (&acc)[2][2][4][2], const Unit& u, int wr, int wc, int fr, int fq) const {
;     ...
;         { const int t = (wr * 4 + wc) * 64 + fq * 16 + fr;
;           if (t < 256) { const int row = u.pm * 254 - 2 + t; const bool ok = row >= 0 && row < 16384; const int rc = ok ? row : 0;
;               const __attribute__((address_space(1))) f32x4* pp = (const __attribute__((address_space(1))) f32x4*)(part + (size_t)rc * 16); const f32x4 a = pp[0], b = pp[1], c = pp[2], d = pp[3];
;               const f32x4 s4 = (a + b) + (c + d); const float ss = (s4[0] + s4[1]) + (s4[2] + s4[3]);
;               rsl[t] = ok ? __builtin_amdgcn_rsqf(ss * (1.0f / 1024.0f) + 1e-6f) : 0.f; } }
.LBB0_80:
	s_mul_i32 s21, s76, 0xfe
	s_and_saveexec_b64 s[56:57], s[38:39]
	v_readlane_b32 s77, v254, 32
	v_readlane_b32 s78, v254, 33
	v_readlane_b32 s79, v254, 34
	v_readlane_b32 s80, v254, 35
	s_movk_i32 s62, 0x4000
	s_cbranch_execz .LBB0_82
	s_cmp_eq_u32 s76, s100
	s_cbranch_scc1 .LBB0_82
	s_mov_b32 s100, s76
	v_add_u32_e32 v116, s21, v191
	v_cmp_gt_u32_e32 vcc, s62, v116
	s_nop 1
	v_cndmask_b32_e32 v116, 0, v116, vcc
	v_ashrrev_i32_e32 v117, 31, v116
	v_lshlrev_b64 v[116:117], 6, v[116:117]
	v_lshl_add_u64 v[140:141], s[6:7], 0, v[116:117]
	global_load_dwordx4 v[116:119], v[140:141], off
	global_load_dwordx4 v[132:135], v[140:141], off offset:16
	global_load_dwordx4 v[136:139], v[140:141], off offset:32
	s_nop 0
	global_load_dwordx4 v[140:143], v[140:141], off offset:48
	s_waitcnt vmcnt(0)
	v_pk_add_f32 v[118:119], v[118:119], v[134:135]
	v_pk_add_f32 v[116:117], v[116:117], v[132:133]
	v_pk_add_f32 v[132:133], v[138:139], v[142:143]
	v_pk_add_f32 v[134:135], v[136:137], v[140:141]
	v_pk_add_f32 v[118:119], v[118:119], v[132:133]
	v_pk_add_f32 v[116:117], v[116:117], v[134:135]
	s_nop 0
	v_pk_mov_b32 v[132:133], v[116:117], v[118:119] op_sel:[1,0]
	v_mov_b32_e32 v117, v119
	v_pk_add_f32 v[116:117], v[132:133], v[116:117]
	s_nop 0
	v_add_f32_e32 v116, v116, v117
	v_fmamk_f32 v116, v116, 0x3a800000, v220
	v_rsq_f32_e32 v116, v116
	s_nop 0
	v_cndmask_b32_e32 v116, 0, v116, vcc
	ds_write_b32 v215, v116

;     __device__ __forceinline__ void operator()(const f32x4 (&acc)[2][2][4][2], const Unit& u, int wr, int wc, int fr, int fq) const {
;         { const int t = (wr * 4 + wc) * 64 + fq * 16 + fr;
;           if (t < 256) { const __attribute__((address_space(1))) f32x4* pp = (const __attribute__((address_space(1))) f32x4*)(part + (size_t)(u.pm * BM + t) * 16); const f32x4 a = pp[0], b = pp[1], c = pp[2], d = pp[3];
;               const f32x4 s4 = (a + b) + (c + d); const float ss = (s4[0] + s4[1]) + (s4[2] + s4[3]); rsl[t] = __builtin_amdgcn_rsqf(ss * (1.0f / 1024.0f) + 1e-6f); } }
.LBB0_307:
	s_lshl_b32 s13, s51, 8
	s_and_saveexec_b64 s[20:21], s[38:39]
	s_cbranch_execz .LBB0_309
	s_cmp_eq_u32 s51, s100
	s_cbranch_scc1 .LBB0_309
	s_mov_b32 s100, s51
	v_add_u32_e32 v138, s13, v144
	v_ashrrev_i32_e32 v139, 31, v138
	v_lshlrev_b64 v[138:139], 6, v[138:139]
	v_lshl_add_u64 v[158:159], s[6:7], 0, v[138:139]
	global_load_dwordx4 v[138:141], v[158:159], off
	global_load_dwordx4 v[150:153], v[158:159], off offset:16
	global_load_dwordx4 v[154:157], v[158:159], off offset:32
	s_nop 0
	global_load_dwordx4 v[158:161], v[158:159], off offset:48
	s_waitcnt vmcnt(0)
	v_pk_add_f32 v[140:141], v[140:141], v[152:153]
	v_pk_add_f32 v[138:139], v[138:139], v[150:151]
	v_pk_add_f32 v[150:151], v[156:157], v[160:161]
	v_pk_add_f32 v[152:153], v[154:155], v[158:159]
	v_pk_add_f32 v[140:141], v[140:141], v[150:151]
	v_pk_add_f32 v[138:139], v[138:139], v[152:153]
	s_nop 0
	v_pk_mov_b32 v[150:151], v[138:139], v[140:141] op_sel:[1,0]
	v_mov_b32_e32 v139, v141
	v_pk_add_f32 v[138:139], v[150:151], v[138:139]
	s_nop 0
	v_add_f32_e32 v138, v138, v139
	v_fmamk_f32 v138, v138, 0x3a800000, v220
	v_rsq_f32_e32 v138, v138
	ds_write_b32 v145, v138

; __device__ __forceinline__ unsigned xb_ld(unsigned* p)              { return __hip_atomic_load(p, __ATOMIC_RELAXED, __HIP_MEMORY_SCOPE_AGENT); }
; __device__ __forceinline__ unsigned xb_add(unsigned* p, unsigned v) { return __hip_atomic_fetch_add(p, v, __ATOMIC_RELAXED, __HIP_MEMORY_SCOPE_AGENT); }
; #define XB_SPIN(cond, bar) do { unsigned _sp = 0; while (cond) { __builtin_amdgcn_s_sleep(1); \
;     if ((++_sp & 255u) == 0u) { if (xb_ld(&(bar)[XB_TMO])) break; if (_sp > XB_SPIN_CAP) { atomicAdd(&(bar)[XB_TMO], 1u); break; } } } } while (0)
; __device__ __forceinline__ void xcd_barrier(const XcdBarrier& b) {
;     ...
;         const unsigned old = xb_add(&bar[XB_XSUB(b.x)], 1u);
;         const unsigned gen = old / nloc;
;         if (old + 1u == (gen + 1u) * nloc) {
;             __builtin_amdgcn_fence(__ATOMIC_RELEASE, "agent");
;             asm volatile("s_waitcnt vmcnt(0)" ::: "memory");
;             const unsigned og = xb_add(&bar[XB_TOP], 1u);
;             const unsigned tg = og / nx;
;             if (og + 1u == (tg + 1u) * nx) xb_add(&bar[XB_TOPGEN], 1u);
;             else XB_SPIN(xb_ld(&bar[XB_TOPGEN]) == tg, bar);
;             __builtin_amdgcn_fence(__ATOMIC_ACQUIRE, "agent");
;             xb_add(&bar[XB_XGEN(b.x)], 1u);
;             asm volatile("s_waitcnt vmcnt(0)" ::: "memory");
;         } else {
;             XB_SPIN(xb_ld(&bar[XB_XGEN(b.x)]) == gen, bar);
.LBB0_380:
	s_or_b64 exec, exec, s[6:7]
	buffer_inv sc1
	v_cvt_f32_u32_e32 v4, v2
	s_waitcnt vmcnt(1)
	v_readfirstlane_b32 s2, v3
	v_sub_u32_e32 v3, 0, v2
	v_rcp_iflag_f32_e32 v4, v4
	v_add_u32_e32 v5, s2, v1
	v_mul_f32_e32 v4, 0x4f7ffffe, v4
	v_cvt_u32_f32_e32 v4, v4
	v_mul_lo_u32 v1, v3, v4
	v_mul_hi_u32 v1, v4, v1
	v_add_u32_e32 v1, v4, v1
	v_mul_hi_u32 v1, v5, v1
	v_mul_lo_u32 v3, v1, v2
	v_sub_u32_e32 v3, v5, v3
	v_add_u32_e32 v4, 1, v1
	v_cmp_ge_u32_e32 vcc, v3, v2
	s_nop 1
	v_cndmask_b32_e32 v1, v1, v4, vcc
	v_sub_u32_e32 v4, v3, v2
	v_cndmask_b32_e32 v3, v3, v4, vcc
	v_add_u32_e32 v4, 1, v1
	v_cmp_ge_u32_e32 vcc, v3, v2
	v_add_u32_e32 v3, 1, v5
	s_nop 0
	v_cndmask_b32_e32 v1, v1, v4, vcc
	v_mul_lo_u32 v4, v2, v1
	v_add_u32_e32 v2, v4, v2
	v_cmp_ne_u32_e32 vcc, v3, v2
	s_and_saveexec_b64 s[6:7], vcc
	s_xor_b64 s[6:7], exec, s[6:7]
	s_cbranch_execz .LBB0_394
	v_readlane_b32 s8, v253, 22
	v_readlane_b32 s9, v253, 23
	s_waitcnt lgkmcnt(0)
	s_nop 3
	global_load_dword v0, v193, s[8:9] sc1
	s_waitcnt vmcnt(0)
	v_cmp_eq_u32_e32 vcc, v0, v1
	s_and_saveexec_b64 s[8:9], vcc
	s_cbranch_execz .LBB0_393
	s_mov_b32 s2, 1
	s_mov_b64 s[10:11], 0
	s_branch .LBB0_384

; __device__ __forceinline__ unsigned xb_ld(unsigned* p)              { return __hip_atomic_load(p, __ATOMIC_RELAXED, __HIP_MEMORY_SCOPE_AGENT); }
; #define XB_SPIN(cond, bar) do { unsigned _sp = 0; while (cond) { __builtin_amdgcn_s_sleep(1); \
;     if ((++_sp & 255u) == 0u) { if (xb_ld(&(bar)[XB_TMO])) break; if (_sp > XB_SPIN_CAP) { atomicAdd(&(bar)[XB_TMO], 1u); break; } } } } while (0)
; __device__ __forceinline__ void xcd_barrier(const XcdBarrier& b) {
;     ...
;             XB_SPIN(xb_ld(&bar[XB_XGEN(b.x)]) == gen, bar);
;             __builtin_amdgcn_fence(__ATOMIC_ACQUIRE, "agent");
;             asm volatile("s_waitcnt vmcnt(0)" ::: "memory");
.LBB0_393:
	s_or_b64 exec, exec, s[8:9]
	s_waitcnt vmcnt(0)
	s_waitcnt vmcnt(0)

; __device__ __forceinline__ unsigned xb_add(unsigned* p, unsigned v) { return __hip_atomic_fetch_add(p, v, __ATOMIC_RELAXED, __HIP_MEMORY_SCOPE_AGENT); }
; __device__ __forceinline__ void xcd_barrier(const XcdBarrier& b) {
;     ...
;             __builtin_amdgcn_fence(__ATOMIC_ACQUIRE, "agent");
;             xb_add(&bar[XB_XGEN(b.x)], 1u);
;             asm volatile("s_waitcnt vmcnt(0)" ::: "memory");
.LBB0_411:
	s_or_b64 exec, exec, s[6:7]
	s_mov_b64 s[6:7], exec
	v_mbcnt_lo_u32_b32 v0, s6, 0
	v_mbcnt_hi_u32_b32 v0, s7, v0
	v_cmp_eq_u32_e32 vcc, 0, v0
	s_waitcnt vmcnt(0)
	s_and_saveexec_b64 s[8:9], vcc
	s_cbranch_execz .LBB0_8
	s_bcnt1_i32_b64 s2, s[6:7]
	v_readlane_b32 s6, v253, 22
	v_mov_b32_e32 v0, s2
	v_readlane_b32 s7, v253, 23
	s_nop 4
	global_atomic_add v193, v0, s[6:7]
	s_branch .LBB0_8

; __global__ void __launch_bounds__(NTHR, 2) hybrid_fwd(Args args) {
	.amdhsa_kernel _Z10hybrid_fwd4Args
		.amdhsa_group_segment_fixed_size 0
		.amdhsa_private_segment_fixed_size 0
		.amdhsa_kernarg_size 384
		.amdhsa_user_sgpr_count 2
		.amdhsa_user_sgpr_dispatch_ptr 0
		.amdhsa_user_sgpr_queue_ptr 0
		.amdhsa_user_sgpr_kernarg_segment_ptr 1
		.amdhsa_user_sgpr_dispatch_id 0
		.amdhsa_user_sgpr_kernarg_preload_length 0
		.amdhsa_user_sgpr_kernarg_preload_offset 0
		.amdhsa_user_sgpr_private_segment_size 0
		.amdhsa_uses_dynamic_stack 0
		.amdhsa_enable_private_segment 0
		.amdhsa_system_sgpr_workgroup_id_x 1
		.amdhsa_system_sgpr_workgroup_id_y 0
		.amdhsa_system_sgpr_workgroup_id_z 0
		.amdhsa_system_sgpr_workgroup_info 0
		.amdhsa_system_vgpr_workitem_id 2
		.amdhsa_next_free_vgpr 256
		.amdhsa_next_free_sgpr 102
		.amdhsa_accum_offset 256
		.amdhsa_reserve_vcc 1
		.amdhsa_float_round_mode_32 0
		.amdhsa_float_round_mode_16_64 0
		.amdhsa_float_denorm_mode_32 3
		.amdhsa_float_denorm_mode_16_64 3
		.amdhsa_dx10_clamp 1
		.amdhsa_ieee_mode 1
		.amdhsa_fp16_overflow 0
		.amdhsa_tg_split 0
		.amdhsa_exception_fp_ieee_invalid_op 0
		.amdhsa_exception_fp_denorm_src 0
		.amdhsa_exception_fp_ieee_div_zero 0
		.amdhsa_exception_fp_ieee_overflow 0
		.amdhsa_exception_fp_ieee_underflow 0
		.amdhsa_exception_fp_ieee_inexact 0
		.amdhsa_exception_int_div_zero 0
	.end_amdhsa_kernel

; __global__ void __launch_bounds__(NTHR, 2) hybrid_fwd(Args args) {
amdhsa.kernels:
  - .agpr_count:     0
    .args:
      - .offset:         0
        .size:           128
        .value_kind:     by_value
      - .offset:         128
        .size:           4
        .value_kind:     hidden_block_count_x
      - .offset:         132
        .size:           4
        .value_kind:     hidden_block_count_y
      - .offset:         136
        .size:           4
        .value_kind:     hidden_block_count_z
      - .offset:         140
        .size:           2
        .value_kind:     hidden_group_size_x
      - .offset:         142
        .size:           2
        .value_kind:     hidden_group_size_y
      - .offset:         144
        .size:           2
        .value_kind:     hidden_group_size_z
      - .offset:         146
        .size:           2
        .value_kind:     hidden_remainder_x
      - .offset:         148
        .size:           2
        .value_kind:     hidden_remainder_y
      - .offset:         150
        .size:           2
        .value_kind:     hidden_remainder_z
      - .offset:         168
        .size:           8
        .value_kind:     hidden_global_offset_x
      - .offset:         176
        .size:           8
        .value_kind:     hidden_global_offset_y
      - .offset:         184
        .size:           8
        .value_kind:     hidden_global_offset_z
      - .offset:         192
        .size:           2
        .value_kind:     hidden_grid_dims
      - .offset:         216
        .size:           8
        .value_kind:     hidden_multigrid_sync_arg
      - .offset:         248
        .size:           4
        .value_kind:     hidden_dynamic_lds_size
    .group_segment_fixed_size: 0
    .kernarg_segment_align: 8
    .kernarg_segment_size: 384
    .language:       OpenCL C
    .language_version:
      - 2
      - 0
    .max_flat_workgroup_size: 512
    .name:           _Z10hybrid_fwd4Args
    .private_segment_fixed_size: 0
    .sgpr_count:     108
    .sgpr_spill_count: 206
    .symbol:         _Z10hybrid_fwd4Args.kd
    .uniform_work_group_size: 1
    .uses_dynamic_stack: false
    .vgpr_count:     256
    .vgpr_spill_count: 0
    .wavefront_size: 64
